# L0 out-proj epilogue (f32 residual x): residual loads of 7 row pieces at a time issued up front with counted vmcnt, same as the other three residual epilogues
# speedup vs baseline: 1.0009x; 1.0009x over previous
; __device__ __forceinline__ unsigned cvt_pk_bf16(float lo, float hi) { unsigned r; asm volatile("v_cvt_pk_bf16_f32 %0, %1, %2" : "=v"(r) : "v"(lo), "v"(hi)); return r; }
;     __device__ __forceinline__ void operator()(const f32x4 (&acc)[2][2][4][2], const Unit& u, int wr, int wc, int fr, int fq) const {
;     ...
;         for (int ai = 0; ai < 2; ++ai)
; #pragma unroll
;             for (int m = 0; m < 4; ++m) { const size_t off = (size_t)(row0 + ai * HALF + m * 16) * ldc + col0;
; #pragma unroll
;                 for (int bj = 0; bj < 2; ++bj) { f32x4 r0, r1;
;                     if constexpr (sizeof(TI) == 4) { r0 = *(const f32x4*)((const float*)res + off + bj * HALF); r1 = *(const f32x4*)((const float*)res + off + bj * HALF + 4); }
;                     else { const u32x4 w = *(const u32x4*)((const bf16_t*)res + off + bj * HALF);
;                         r0 = (f32x4){__uint_as_float(w.x << 16), __uint_as_float(w.x & 0xffff0000u), __uint_as_float(w.y << 16), __uint_as_float(w.y & 0xffff0000u)};
;                         r1 = (f32x4){__uint_as_float(w.z << 16), __uint_as_float(w.z & 0xffff0000u), __uint_as_float(w.w << 16), __uint_as_float(w.w & 0xffff0000u)}; }
;                     const f32x4 o0 = r0 + gv[bj][0] * acc[ai][bj][m][0], o1 = r1 + gv[bj][1] * acc[ai][bj][m][1];
;                     if constexpr (sizeof(TO) == 4) { *(f32x4*)((float*)out + off + bj * HALF) = o0; *(f32x4*)((float*)out + off + bj * HALF + 4) = o1; }
;                     else { u32x4 w; w.x = cvt_pk_bf16(o0[0], o0[1]); w.y = cvt_pk_bf16(o0[2], o0[3]); w.z = cvt_pk_bf16(o1[0], o1[1]); w.w = cvt_pk_bf16(o1[2], o1[3]); *(u32x4*)((bf16_t*)out + off + bj * HALF) = w; } }
;                 asm volatile("" ::: "memory"); }
.LBB0_356:
	s_ashr_i32 s27, s36, 31
	s_lshr_b32 s27, s27, 28
	s_add_i32 s27, s36, s27
	s_ashr_i32 s27, s27, 4
	v_lshl_add_u32 v164, s36, 8, v166
	v_lshl_or_b32 v162, s48, 8, v168
	s_mul_hi_i32 s29, s27, 0xc000
	s_mul_i32 s27, s27, 0xc000
	v_ashrrev_i32_e32 v165, 31, v164
	s_add_u32 s50, s66, s27
	v_ashrrev_i32_e32 v163, 31, v162
	v_lshlrev_b64 v[132:133], 11, v[164:165]
	s_addc_u32 s51, s67, s29
	v_lshl_add_u64 v[160:161], v[132:133], 0, v[162:163]
	v_lshl_add_u64 v[136:137], v[162:163], 2, s[50:51]
	v_lshl_add_u64 v[180:181], v[160:161], 2, s[8:9]
	global_load_dwordx4 v[128:131], v[136:137], off
	global_load_dwordx4 v[172:175], v[180:181], off
	global_load_dwordx4 v[176:179], v[180:181], off offset:16
	global_load_dwordx4 v[132:135], v[136:137], off offset:16
	v_lshl_add_u64 v[182:183], v[160:161], 1, s[12:13]
	global_load_dwordx4 v[140:143], v[136:137], off offset:512
	s_nop 0
	global_load_dwordx4 v[136:139], v[136:137], off offset:528
	global_load_dwordx4 v[184:187], v[180:181], off offset:512
	global_load_dwordx4 v[188:191], v[180:181], off offset:528
	s_mov_b32 s92, 0x20000
	s_mov_b32 s93, 0
	v_lshl_add_u64 v[250:251], v[180:181], 0, s[92:93]
	global_load_dwordx4 v[194:197], v[250:251], off
	global_load_dwordx4 v[198:201], v[250:251], off offset:16
	s_mov_b32 s92, 0x20000
	s_mov_b32 s93, 0
	v_lshl_add_u64 v[250:251], v[180:181], 0, s[92:93]
	global_load_dwordx4 v[202:205], v[250:251], off offset:512
	global_load_dwordx4 v[206:209], v[250:251], off offset:528
	s_mov_b32 s92, 0x40000
	s_mov_b32 s93, 0
	v_lshl_add_u64 v[250:251], v[180:181], 0, s[92:93]
	global_load_dwordx4 v[210:213], v[250:251], off
	global_load_dwordx4 v[214:217], v[250:251], off offset:16
	s_mov_b32 s92, 0x40000
	s_mov_b32 s93, 0
	v_lshl_add_u64 v[250:251], v[180:181], 0, s[92:93]
	global_load_dwordx4 v[226:229], v[250:251], off offset:512
	global_load_dwordx4 v[230:233], v[250:251], off offset:528
	s_mov_b32 s92, 0x60000
	s_mov_b32 s93, 0
	v_lshl_add_u64 v[250:251], v[180:181], 0, s[92:93]
	global_load_dwordx4 v[234:237], v[250:251], off
	global_load_dwordx4 v[238:241], v[250:251], off offset:16
	s_mov_b32 s92, 0x60000
	s_mov_b32 s93, 0
	v_lshl_add_u64 v[250:251], v[180:181], 0, s[92:93]
	global_load_dwordx4 v[242:245], v[250:251], off offset:512
	global_load_dwordx4 v[246:249], v[250:251], off offset:528
	s_andn2_b64 vcc, exec, s[6:7]
	s_mov_b64 s[6:7], -1
	s_waitcnt vmcnt(14)
	v_pk_fma_f32 v[124:125], v[124:125], v[128:129], v[172:173]
	v_pk_fma_f32 v[172:173], v[122:123], v[134:135], v[178:179]
	v_pk_fma_f32 v[122:123], v[120:121], v[132:133], v[176:177]
	v_pk_fma_f32 v[126:127], v[126:127], v[130:131], v[174:175]
	v_cvt_pk_bf16_f32 v120, v124, v125
	s_nop 0
	v_cvt_pk_bf16_f32 v121, v126, v127
	v_cvt_pk_bf16_f32 v122, v122, v123
	v_cvt_pk_bf16_f32 v123, v172, v173
	global_store_dwordx4 v[182:183], v[120:123], off
	s_nop 0
	s_nop 0
	s_nop 0
	v_or_b32_e32 v172, 16, v164
	v_ashrrev_i32_e32 v173, 31, v172
	v_lshlrev_b64 v[172:173], 11, v[172:173]
	v_lshl_add_u64 v[172:173], v[172:173], 0, v[162:163]
	v_lshl_add_u64 v[174:175], v[172:173], 2, s[8:9]
	s_waitcnt vmcnt(13)
	v_pk_fma_f32 v[116:117], v[116:117], v[140:141], v[184:185]
	v_pk_fma_f32 v[120:121], v[114:115], v[138:139], v[190:191]
	v_pk_fma_f32 v[114:115], v[112:113], v[136:137], v[188:189]
	v_pk_fma_f32 v[118:119], v[118:119], v[142:143], v[186:187]
	v_cvt_pk_bf16_f32 v112, v116, v117
	s_nop 0
	v_cvt_pk_bf16_f32 v113, v118, v119
	v_cvt_pk_bf16_f32 v114, v114, v115
	v_cvt_pk_bf16_f32 v115, v120, v121
	global_store_dwordx4 v[182:183], v[112:115], off offset:256
	s_nop 0
	s_nop 0
	v_lshl_add_u64 v[120:121], v[172:173], 1, s[12:13]
	s_waitcnt vmcnt(12)
	v_pk_fma_f32 v[108:109], v[108:109], v[128:129], v[194:195]
	v_pk_fma_f32 v[112:113], v[106:107], v[134:135], v[200:201]
	v_pk_fma_f32 v[106:107], v[104:105], v[132:133], v[198:199]
	v_pk_fma_f32 v[110:111], v[110:111], v[130:131], v[196:197]
	v_cvt_pk_bf16_f32 v104, v108, v109
	s_nop 0
	v_cvt_pk_bf16_f32 v105, v110, v111
	v_cvt_pk_bf16_f32 v106, v106, v107
	v_cvt_pk_bf16_f32 v107, v112, v113
	global_store_dwordx4 v[120:121], v[104:107], off
	s_nop 0
	s_nop 0
	s_nop 0
	v_or_b32_e32 v112, 32, v164
	v_ashrrev_i32_e32 v113, 31, v112
	v_lshlrev_b64 v[112:113], 11, v[112:113]
	v_lshl_add_u64 v[112:113], v[112:113], 0, v[162:163]
	v_lshl_add_u64 v[114:115], v[112:113], 2, s[8:9]
	s_waitcnt vmcnt(11)
	v_pk_fma_f32 v[100:101], v[100:101], v[140:141], v[202:203]
	v_pk_fma_f32 v[104:105], v[98:99], v[138:139], v[208:209]
	v_pk_fma_f32 v[98:99], v[96:97], v[136:137], v[206:207]
	v_pk_fma_f32 v[102:103], v[102:103], v[142:143], v[204:205]
	v_cvt_pk_bf16_f32 v96, v100, v101
	s_nop 0
	v_cvt_pk_bf16_f32 v97, v102, v103
	v_cvt_pk_bf16_f32 v98, v98, v99
	v_cvt_pk_bf16_f32 v99, v104, v105
	global_store_dwordx4 v[120:121], v[96:99], off offset:256
	s_nop 0
	s_nop 0
	v_lshl_add_u64 v[104:105], v[112:113], 1, s[12:13]
	s_waitcnt vmcnt(10)
	v_pk_fma_f32 v[92:93], v[92:93], v[128:129], v[210:211]
	v_pk_fma_f32 v[96:97], v[90:91], v[134:135], v[216:217]
	v_pk_fma_f32 v[90:91], v[88:89], v[132:133], v[214:215]
	v_pk_fma_f32 v[94:95], v[94:95], v[130:131], v[212:213]
	v_cvt_pk_bf16_f32 v88, v92, v93
	s_nop 0
	v_cvt_pk_bf16_f32 v89, v94, v95
	v_cvt_pk_bf16_f32 v90, v90, v91
	v_cvt_pk_bf16_f32 v91, v96, v97
	global_store_dwordx4 v[104:105], v[88:91], off
	s_nop 0
	s_nop 0
	s_nop 0
	v_or_b32_e32 v96, 48, v164
	v_ashrrev_i32_e32 v97, 31, v96
	v_lshlrev_b64 v[96:97], 11, v[96:97]
	v_lshl_add_u64 v[96:97], v[96:97], 0, v[162:163]
	v_lshl_add_u64 v[98:99], v[96:97], 2, s[8:9]
	s_waitcnt vmcnt(9)
; __device__ __forceinline__ unsigned cvt_pk_bf16(float lo, float hi) { unsigned r; asm volatile("v_cvt_pk_bf16_f32 %0, %1, %2" : "=v"(r) : "v"(lo), "v"(hi)); return r; }
;     __device__ __forceinline__ void operator()(const f32x4 (&acc)[2][2][4][2], const Unit& u, int wr, int wc, int fr, int fq) const {
;     ...
;         for (int ai = 0; ai < 2; ++ai)
; #pragma unroll
;             for (int m = 0; m < 4; ++m) { const size_t off = (size_t)(row0 + ai * HALF + m * 16) * ldc + col0;
; #pragma unroll
;                 for (int bj = 0; bj < 2; ++bj) { f32x4 r0, r1;
;                     if constexpr (sizeof(TI) == 4) { r0 = *(const f32x4*)((const float*)res + off + bj * HALF); r1 = *(const f32x4*)((const float*)res + off + bj * HALF + 4); }
;                     else { const u32x4 w = *(const u32x4*)((const bf16_t*)res + off + bj * HALF);
;                         r0 = (f32x4){__uint_as_float(w.x << 16), __uint_as_float(w.x & 0xffff0000u), __uint_as_float(w.y << 16), __uint_as_float(w.y & 0xffff0000u)};
;                         r1 = (f32x4){__uint_as_float(w.z << 16), __uint_as_float(w.z & 0xffff0000u), __uint_as_float(w.w << 16), __uint_as_float(w.w & 0xffff0000u)}; }
;                     const f32x4 o0 = r0 + gv[bj][0] * acc[ai][bj][m][0], o1 = r1 + gv[bj][1] * acc[ai][bj][m][1];
;                     if constexpr (sizeof(TO) == 4) { *(f32x4*)((float*)out + off + bj * HALF) = o0; *(f32x4*)((float*)out + off + bj * HALF + 4) = o1; }
;                     else { u32x4 w; w.x = cvt_pk_bf16(o0[0], o0[1]); w.y = cvt_pk_bf16(o0[2], o0[3]); w.z = cvt_pk_bf16(o1[0], o1[1]); w.w = cvt_pk_bf16(o1[2], o1[3]); *(u32x4*)((bf16_t*)out + off + bj * HALF) = w; } }
;                 asm volatile("" ::: "memory"); }
	v_pk_fma_f32 v[84:85], v[84:85], v[140:141], v[226:227]
	v_pk_fma_f32 v[88:89], v[82:83], v[138:139], v[232:233]
	v_pk_fma_f32 v[82:83], v[80:81], v[136:137], v[230:231]
	v_pk_fma_f32 v[86:87], v[86:87], v[142:143], v[228:229]
	v_cvt_pk_bf16_f32 v80, v84, v85
	s_nop 0
	v_cvt_pk_bf16_f32 v81, v86, v87
	v_cvt_pk_bf16_f32 v82, v82, v83
	v_cvt_pk_bf16_f32 v83, v88, v89
	global_store_dwordx4 v[104:105], v[80:83], off offset:256
	s_nop 0
	s_nop 0
	v_lshl_add_u64 v[88:89], v[96:97], 1, s[12:13]
	s_waitcnt vmcnt(8)
	v_pk_fma_f32 v[76:77], v[76:77], v[128:129], v[234:235]
	v_pk_fma_f32 v[80:81], v[74:75], v[134:135], v[240:241]
	v_pk_fma_f32 v[74:75], v[72:73], v[132:133], v[238:239]
	v_pk_fma_f32 v[78:79], v[78:79], v[130:131], v[236:237]
	v_cvt_pk_bf16_f32 v72, v76, v77
	s_nop 0
	v_cvt_pk_bf16_f32 v73, v78, v79
	v_cvt_pk_bf16_f32 v74, v74, v75
	v_cvt_pk_bf16_f32 v75, v80, v81
	global_store_dwordx4 v[88:89], v[72:75], off
	s_nop 0
	s_nop 0
	s_nop 0
	v_lshl_add_u64 v[80:81], v[160:161], 0, s[18:19]
	v_lshl_add_u64 v[82:83], v[80:81], 2, s[8:9]
	s_waitcnt vmcnt(7)
	v_pk_fma_f32 v[68:69], v[68:69], v[140:141], v[242:243]
	v_pk_fma_f32 v[72:73], v[66:67], v[138:139], v[248:249]
	v_pk_fma_f32 v[66:67], v[64:65], v[136:137], v[246:247]
	v_pk_fma_f32 v[70:71], v[70:71], v[142:143], v[244:245]
	v_cvt_pk_bf16_f32 v64, v68, v69
	s_nop 0
	v_cvt_pk_bf16_f32 v65, v70, v71
	v_cvt_pk_bf16_f32 v66, v66, v67
	v_cvt_pk_bf16_f32 v67, v72, v73
	global_store_dwordx4 v[88:89], v[64:67], off offset:256
	s_mov_b32 s92, 0x100000
	s_mov_b32 s93, 0
	v_lshl_add_u64 v[250:251], v[180:181], 0, s[92:93]
	global_load_dwordx4 v[184:187], v[250:251], off
	global_load_dwordx4 v[188:191], v[250:251], off offset:16
	s_mov_b32 s92, 0x100000
	s_mov_b32 s93, 0
	v_lshl_add_u64 v[250:251], v[180:181], 0, s[92:93]
	global_load_dwordx4 v[194:197], v[250:251], off offset:512
	global_load_dwordx4 v[198:201], v[250:251], off offset:528
	s_mov_b32 s92, 0x120000
	s_mov_b32 s93, 0
	v_lshl_add_u64 v[250:251], v[180:181], 0, s[92:93]
	global_load_dwordx4 v[202:205], v[250:251], off
	global_load_dwordx4 v[206:209], v[250:251], off offset:16
	s_mov_b32 s92, 0x120000
	s_mov_b32 s93, 0
	v_lshl_add_u64 v[250:251], v[180:181], 0, s[92:93]
	global_load_dwordx4 v[210:213], v[250:251], off offset:512
	global_load_dwordx4 v[214:217], v[250:251], off offset:528
	s_mov_b32 s92, 0x140000
	s_mov_b32 s93, 0
	v_lshl_add_u64 v[250:251], v[180:181], 0, s[92:93]
	global_load_dwordx4 v[226:229], v[250:251], off
	global_load_dwordx4 v[230:233], v[250:251], off offset:16
	s_mov_b32 s92, 0x140000
	s_mov_b32 s93, 0
	v_lshl_add_u64 v[250:251], v[180:181], 0, s[92:93]
	global_load_dwordx4 v[234:237], v[250:251], off offset:512
	global_load_dwordx4 v[238:241], v[250:251], off offset:528
	s_mov_b32 s92, 0x160000
	s_mov_b32 s93, 0
	v_lshl_add_u64 v[250:251], v[180:181], 0, s[92:93]
	global_load_dwordx4 v[242:245], v[250:251], off
	global_load_dwordx4 v[246:249], v[250:251], off offset:16
	s_nop 0
	s_nop 0
	v_lshl_add_u64 v[72:73], v[80:81], 1, s[12:13]
	s_waitcnt vmcnt(12)
	v_pk_fma_f32 v[60:61], v[60:61], v[128:129], v[184:185]
	v_pk_fma_f32 v[64:65], v[58:59], v[134:135], v[190:191]
	v_pk_fma_f32 v[58:59], v[56:57], v[132:133], v[188:189]
	v_pk_fma_f32 v[62:63], v[62:63], v[130:131], v[186:187]
	v_cvt_pk_bf16_f32 v56, v60, v61
	s_nop 0
	v_cvt_pk_bf16_f32 v57, v62, v63
	v_cvt_pk_bf16_f32 v58, v58, v59
	v_cvt_pk_bf16_f32 v59, v64, v65
	global_store_dwordx4 v[72:73], v[56:59], off
	s_nop 0
	s_nop 0
	s_nop 0
	v_lshl_add_u64 v[64:65], v[160:161], 0, s[20:21]
	v_lshl_add_u64 v[66:67], v[64:65], 2, s[8:9]
	s_waitcnt vmcnt(11)
; __device__ __forceinline__ unsigned cvt_pk_bf16(float lo, float hi) { unsigned r; asm volatile("v_cvt_pk_bf16_f32 %0, %1, %2" : "=v"(r) : "v"(lo), "v"(hi)); return r; }
;     __device__ __forceinline__ void operator()(const f32x4 (&acc)[2][2][4][2], const Unit& u, int wr, int wc, int fr, int fq) const {
;     ...
;         for (int ai = 0; ai < 2; ++ai)
; #pragma unroll
;             for (int m = 0; m < 4; ++m) { const size_t off = (size_t)(row0 + ai * HALF + m * 16) * ldc + col0;
; #pragma unroll
;                 for (int bj = 0; bj < 2; ++bj) { f32x4 r0, r1;
;                     if constexpr (sizeof(TI) == 4) { r0 = *(const f32x4*)((const float*)res + off + bj * HALF); r1 = *(const f32x4*)((const float*)res + off + bj * HALF + 4); }
;                     else { const u32x4 w = *(const u32x4*)((const bf16_t*)res + off + bj * HALF);
;                         r0 = (f32x4){__uint_as_float(w.x << 16), __uint_as_float(w.x & 0xffff0000u), __uint_as_float(w.y << 16), __uint_as_float(w.y & 0xffff0000u)};
;                         r1 = (f32x4){__uint_as_float(w.z << 16), __uint_as_float(w.z & 0xffff0000u), __uint_as_float(w.w << 16), __uint_as_float(w.w & 0xffff0000u)}; }
;                     const f32x4 o0 = r0 + gv[bj][0] * acc[ai][bj][m][0], o1 = r1 + gv[bj][1] * acc[ai][bj][m][1];
;                     if constexpr (sizeof(TO) == 4) { *(f32x4*)((float*)out + off + bj * HALF) = o0; *(f32x4*)((float*)out + off + bj * HALF + 4) = o1; }
;                     else { u32x4 w; w.x = cvt_pk_bf16(o0[0], o0[1]); w.y = cvt_pk_bf16(o0[2], o0[3]); w.z = cvt_pk_bf16(o1[0], o1[1]); w.w = cvt_pk_bf16(o1[2], o1[3]); *(u32x4*)((bf16_t*)out + off + bj * HALF) = w; } }
;                 asm volatile("" ::: "memory"); }
	v_pk_fma_f32 v[52:53], v[52:53], v[140:141], v[194:195]
	v_pk_fma_f32 v[56:57], v[50:51], v[138:139], v[200:201]
	v_pk_fma_f32 v[50:51], v[48:49], v[136:137], v[198:199]
	v_pk_fma_f32 v[54:55], v[54:55], v[142:143], v[196:197]
	v_cvt_pk_bf16_f32 v48, v52, v53
	s_nop 0
	v_cvt_pk_bf16_f32 v49, v54, v55
	v_cvt_pk_bf16_f32 v50, v50, v51
	v_cvt_pk_bf16_f32 v51, v56, v57
	global_store_dwordx4 v[72:73], v[48:51], off offset:256
	s_nop 0
	s_nop 0
	v_lshl_add_u64 v[56:57], v[64:65], 1, s[12:13]
	s_waitcnt vmcnt(10)
	v_pk_fma_f32 v[44:45], v[44:45], v[128:129], v[202:203]
	v_pk_fma_f32 v[48:49], v[42:43], v[134:135], v[208:209]
	v_pk_fma_f32 v[42:43], v[40:41], v[132:133], v[206:207]
	v_pk_fma_f32 v[46:47], v[46:47], v[130:131], v[204:205]
	v_cvt_pk_bf16_f32 v40, v44, v45
	s_nop 0
	v_cvt_pk_bf16_f32 v41, v46, v47
	v_cvt_pk_bf16_f32 v42, v42, v43
	v_cvt_pk_bf16_f32 v43, v48, v49
	global_store_dwordx4 v[56:57], v[40:43], off
	s_nop 0
	s_nop 0
	s_nop 0
	v_lshl_add_u64 v[48:49], v[160:161], 0, s[22:23]
	v_lshl_add_u64 v[50:51], v[48:49], 2, s[8:9]
	s_waitcnt vmcnt(9)
	v_pk_fma_f32 v[36:37], v[36:37], v[140:141], v[210:211]
	v_pk_fma_f32 v[40:41], v[34:35], v[138:139], v[216:217]
	v_pk_fma_f32 v[34:35], v[32:33], v[136:137], v[214:215]
	v_pk_fma_f32 v[38:39], v[38:39], v[142:143], v[212:213]
	v_cvt_pk_bf16_f32 v32, v36, v37
	s_nop 0
	v_cvt_pk_bf16_f32 v33, v38, v39
	v_cvt_pk_bf16_f32 v34, v34, v35
	v_cvt_pk_bf16_f32 v35, v40, v41
	global_store_dwordx4 v[56:57], v[32:35], off offset:256
	s_nop 0
	s_nop 0
	v_lshl_add_u64 v[40:41], v[48:49], 1, s[12:13]
	s_waitcnt vmcnt(8)
	v_pk_fma_f32 v[28:29], v[28:29], v[128:129], v[226:227]
	v_pk_fma_f32 v[32:33], v[26:27], v[134:135], v[232:233]
	v_pk_fma_f32 v[26:27], v[24:25], v[132:133], v[230:231]
	v_pk_fma_f32 v[30:31], v[30:31], v[130:131], v[228:229]
	v_cvt_pk_bf16_f32 v24, v28, v29
	s_nop 0
	v_cvt_pk_bf16_f32 v25, v30, v31
	v_cvt_pk_bf16_f32 v26, v26, v27
	v_cvt_pk_bf16_f32 v27, v32, v33
	global_store_dwordx4 v[40:41], v[24:27], off
	s_nop 0
	s_nop 0
	s_nop 0
	v_lshl_add_u64 v[32:33], v[160:161], 0, s[24:25]
	v_lshl_add_u64 v[34:35], v[32:33], 2, s[8:9]
	s_waitcnt vmcnt(7)
	v_pk_fma_f32 v[20:21], v[20:21], v[140:141], v[234:235]
	v_pk_fma_f32 v[24:25], v[18:19], v[138:139], v[240:241]
	v_pk_fma_f32 v[18:19], v[16:17], v[136:137], v[238:239]
	v_pk_fma_f32 v[22:23], v[22:23], v[142:143], v[236:237]
	v_cvt_pk_bf16_f32 v16, v20, v21
	s_nop 0
	v_cvt_pk_bf16_f32 v17, v22, v23
	v_cvt_pk_bf16_f32 v18, v18, v19
	v_cvt_pk_bf16_f32 v19, v24, v25
	global_store_dwordx4 v[40:41], v[16:19], off offset:256
	s_nop 0
	s_nop 0
	v_lshl_add_u64 v[24:25], v[32:33], 1, s[12:13]
	s_waitcnt vmcnt(6)
	v_pk_fma_f32 v[12:13], v[12:13], v[128:129], v[242:243]
	v_pk_fma_f32 v[16:17], v[10:11], v[134:135], v[248:249]
	v_pk_fma_f32 v[10:11], v[8:9], v[132:133], v[246:247]
	v_pk_fma_f32 v[14:15], v[14:15], v[130:131], v[244:245]
	v_cvt_pk_bf16_f32 v8, v12, v13
	s_nop 0
	v_cvt_pk_bf16_f32 v9, v14, v15
	v_cvt_pk_bf16_f32 v10, v10, v11
	v_cvt_pk_bf16_f32 v11, v16, v17
	global_store_dwordx4 v[24:25], v[8:11], off
	global_load_dwordx4 v[8:11], v[34:35], off offset:512
	s_nop 0
	global_load_dwordx4 v[12:15], v[34:35], off offset:528
	s_waitcnt vmcnt(0)
	v_pk_fma_f32 v[4:5], v[4:5], v[140:141], v[8:9]
	v_pk_fma_f32 v[8:9], v[2:3], v[138:139], v[14:15]
	v_pk_fma_f32 v[2:3], v[0:1], v[136:137], v[12:13]
	v_pk_fma_f32 v[6:7], v[6:7], v[142:143], v[10:11]
	v_cvt_pk_bf16_f32 v0, v4, v5
	s_nop 0
	v_cvt_pk_bf16_f32 v1, v6, v7
	v_cvt_pk_bf16_f32 v2, v2, v3
	v_cvt_pk_bf16_f32 v3, v8, v9
	global_store_dwordx4 v[24:25], v[0:3], off offset:256
	s_cbranch_vccnz .LBB0_345
	s_andn2_b64 vcc, exec, s[10:11]
	s_cbranch_vccnz .LBB0_344
	s_barrier
	s_branch .LBB0_344
